# sample attention: the eight permutation-table lookups of a loop trip issued together at the loop top (one LDS wait instead of eight); on top of v18
# speedup vs baseline: 1.0080x; 1.0028x over previous
.LBB0_1251:
	v_subrev_u32_e32 v255, 56, v223
	v_min_i32_e32 v255, 0x187, v255
	v_lshl_add_u32 v255, v255, 2, s101
	ds_read_b32 v246, v255
	v_subrev_u32_e32 v255, 48, v223
	v_min_i32_e32 v255, 0x187, v255
	v_lshl_add_u32 v255, v255, 2, s101
	ds_read_b32 v247, v255
	v_subrev_u32_e32 v255, 40, v223
	v_min_i32_e32 v255, 0x187, v255
	v_lshl_add_u32 v255, v255, 2, s101
	ds_read_b32 v248, v255
	v_subrev_u32_e32 v255, 32, v223
	v_min_i32_e32 v255, 0x187, v255
	v_lshl_add_u32 v255, v255, 2, s101
	ds_read_b32 v249, v255
	v_subrev_u32_e32 v255, 24, v223
	v_min_i32_e32 v255, 0x187, v255
	v_lshl_add_u32 v255, v255, 2, s101
	ds_read_b32 v250, v255
	v_subrev_u32_e32 v255, 16, v223
	v_min_i32_e32 v255, 0x187, v255
	v_lshl_add_u32 v255, v255, 2, s101
	ds_read_b32 v251, v255
	v_subrev_u32_e32 v255, 8, v223
	v_min_i32_e32 v255, 0x187, v255
	v_lshl_add_u32 v255, v255, 2, s101
	ds_read_b32 v252, v255
	v_min_i32_e32 v255, 0x187, v223
	v_lshl_add_u32 v255, v255, 2, s101
	ds_read_b32 v253, v255
	s_waitcnt lgkmcnt(0)
	v_subrev_u32_e32 v66, 56, v223
	v_mov_b32_e32 v66, v246
	v_cmp_lt_i32_e32 vcc, s19, v66
	v_min_i32_e32 v54, 0x182, v66
	s_nop 0
	v_cndmask_b32_e64 v55, 0, 1, vcc
	v_cmp_gt_i32_e32 vcc, s24, v66
	s_nop 1
	v_cndmask_b32_e32 v55, 2, v55, vcc
	v_mul_i32_i24_e32 v56, 0xffffff7f, v55
	v_lshlrev_b32_e32 v55, 1, v55
	v_add_lshl_u32 v54, v56, v54, v55
	v_sub_u32_e32 v156, s18, v54
	v_cmp_lt_i32_e32 vcc, s25, v156
	v_cmp_gt_i32_e64 s[0:1], s17, v156
	s_and_saveexec_b64 s[14:15], s[0:1]
	s_xor_b64 s[0:1], exec, s[14:15]
	v_ashrrev_i32_e32 v55, 31, v156
	v_mov_b32_e32 v54, v156
	v_lshlrev_b64 v[56:57], 11, v[54:55]
	v_lshl_add_u64 v[54:55], v[194:195], 0, v[56:57]
	s_andn2_saveexec_b64 s[0:1], s[0:1]
	v_add_u32_e32 v54, 0xfffff800, v156
	v_mad_u64_u32 v[54:55], s[14:15], v54, s26, v[198:199]
	v_lshlrev_b64 v[56:57], 11, v[156:157]
	s_or_b64 exec, exec, s[0:1]
	v_lshl_add_u64 v[62:63], v[54:55], 0, s[38:39]
	v_lshl_add_u64 v[56:57], v[200:201], 0, v[56:57]
	v_cndmask_b32_e32 v63, v57, v63, vcc
	v_cndmask_b32_e32 v62, v56, v62, vcc
	v_min_i32_e32 v66, 0x187, v66
	global_load_dwordx4 v[102:105], v[54:55], off offset:16
	global_load_dwordx4 v[114:117], v[54:55], off
	s_nop 0
	global_load_dwordx4 v[54:57], v[62:63], off offset:16
	s_nop 0
	global_load_dwordx4 v[62:65], v[62:63], off
	v_ashrrev_i32_e32 v67, 31, v66
	v_lshl_add_u64 v[66:67], v[66:67], 2, s[40:41]
	global_load_dword v229, v[66:67], off
	v_subrev_u32_e32 v82, 48, v223
	v_mov_b32_e32 v82, v247
	v_cmp_lt_i32_e32 vcc, s19, v82
	v_min_i32_e32 v66, 0x182, v82
	s_nop 0
	v_cndmask_b32_e64 v67, 0, 1, vcc
	v_cmp_gt_i32_e32 vcc, s24, v82
	s_nop 1
	v_cndmask_b32_e32 v67, 2, v67, vcc
	v_mul_i32_i24_e32 v68, 0xffffff7f, v67
	v_lshlrev_b32_e32 v67, 1, v67
	v_add_lshl_u32 v66, v68, v66, v67
	v_sub_u32_e32 v68, s18, v66
	v_cmp_lt_i32_e32 vcc, s25, v68
	v_cmp_gt_i32_e64 s[0:1], s17, v68
	s_and_saveexec_b64 s[14:15], s[0:1]
	s_xor_b64 s[0:1], exec, s[14:15]
	v_ashrrev_i32_e32 v69, 31, v68
	v_lshlrev_b64 v[78:79], 11, v[68:69]
	v_lshl_add_u64 v[66:67], v[194:195], 0, v[78:79]
	s_andn2_saveexec_b64 s[0:1], s[0:1]
	v_add_u32_e32 v66, 0xfffff800, v68
	v_mov_b32_e32 v69, v157
	v_mad_u64_u32 v[66:67], s[14:15], v66, s26, v[198:199]
	v_lshlrev_b64 v[78:79], 11, v[68:69]
	s_or_b64 exec, exec, s[0:1]
	v_lshl_add_u64 v[68:69], v[66:67], 0, s[38:39]
	v_lshl_add_u64 v[78:79], v[200:201], 0, v[78:79]
	v_cndmask_b32_e32 v79, v79, v69, vcc
	v_cndmask_b32_e32 v78, v78, v68, vcc
	v_min_i32_e32 v82, 0x187, v82
	global_load_dwordx4 v[118:121], v[66:67], off offset:16
	global_load_dwordx4 v[122:125], v[66:67], off
	s_nop 0
	global_load_dwordx4 v[66:69], v[78:79], off offset:16
	s_nop 0
	global_load_dwordx4 v[78:81], v[78:79], off
	v_ashrrev_i32_e32 v83, 31, v82
	v_lshl_add_u64 v[82:83], v[82:83], 2, s[40:41]
	global_load_dword v230, v[82:83], off
	v_subrev_u32_e32 v90, 40, v223
	v_mov_b32_e32 v90, v248
	v_cmp_lt_i32_e32 vcc, s19, v90
	v_min_i32_e32 v82, 0x182, v90
	s_nop 0
	v_cndmask_b32_e64 v83, 0, 1, vcc
	v_cmp_gt_i32_e32 vcc, s24, v90
	s_nop 1
	v_cndmask_b32_e32 v83, 2, v83, vcc
	v_mul_i32_i24_e32 v84, 0xffffff7f, v83
	v_lshlrev_b32_e32 v83, 1, v83
	v_add_lshl_u32 v82, v84, v82, v83
	v_sub_u32_e32 v84, s18, v82
	v_cmp_lt_i32_e32 vcc, s25, v84
	v_cmp_gt_i32_e64 s[0:1], s17, v84
	s_and_saveexec_b64 s[14:15], s[0:1]
	s_xor_b64 s[0:1], exec, s[14:15]
	v_ashrrev_i32_e32 v85, 31, v84
	v_lshlrev_b64 v[86:87], 11, v[84:85]
	v_lshl_add_u64 v[82:83], v[194:195], 0, v[86:87]
	s_andn2_saveexec_b64 s[0:1], s[0:1]
	v_add_u32_e32 v82, 0xfffff800, v84
	v_mov_b32_e32 v85, v157
	v_mad_u64_u32 v[82:83], s[14:15], v82, s26, v[198:199]
	v_lshlrev_b64 v[86:87], 11, v[84:85]
	s_or_b64 exec, exec, s[0:1]
	v_lshl_add_u64 v[84:85], v[82:83], 0, s[38:39]
	v_lshl_add_u64 v[86:87], v[200:201], 0, v[86:87]
	v_cndmask_b32_e32 v85, v87, v85, vcc
	v_cndmask_b32_e32 v84, v86, v84, vcc
	global_load_dwordx4 v[134:137], v[82:83], off offset:16
	global_load_dwordx4 v[138:141], v[82:83], off
	global_load_dwordx4 v[86:89], v[84:85], off offset:16
	global_load_dwordx4 v[94:97], v[84:85], off
	v_min_i32_e32 v82, 0x187, v90
	v_ashrrev_i32_e32 v83, 31, v82
	v_lshl_add_u64 v[82:83], v[82:83], 2, s[40:41]
	global_load_dword v231, v[82:83], off
	v_subrev_u32_e32 v92, 32, v223
	v_mov_b32_e32 v92, v249
	v_cmp_lt_i32_e32 vcc, s19, v92
	v_min_i32_e32 v82, 0x182, v92
	s_nop 0
	v_cndmask_b32_e64 v83, 0, 1, vcc
	v_cmp_gt_i32_e32 vcc, s24, v92
	s_nop 1
	v_cndmask_b32_e32 v83, 2, v83, vcc
	v_mul_i32_i24_e32 v84, 0xffffff7f, v83
	v_lshlrev_b32_e32 v83, 1, v83
	v_add_lshl_u32 v82, v84, v82, v83
	v_sub_u32_e32 v84, s18, v82
	v_cmp_lt_i32_e32 vcc, s25, v84
	v_cmp_gt_i32_e64 s[0:1], s17, v84
	s_and_saveexec_b64 s[14:15], s[0:1]
	s_xor_b64 s[0:1], exec, s[14:15]
	v_ashrrev_i32_e32 v85, 31, v84
	v_lshlrev_b64 v[90:91], 11, v[84:85]
	v_lshl_add_u64 v[82:83], v[194:195], 0, v[90:91]
	s_andn2_saveexec_b64 s[0:1], s[0:1]
	v_add_u32_e32 v82, 0xfffff800, v84
	v_mov_b32_e32 v85, v157
	v_mad_u64_u32 v[82:83], s[14:15], v82, s26, v[198:199]
	v_lshlrev_b64 v[90:91], 11, v[84:85]
	s_or_b64 exec, exec, s[0:1]
	v_lshl_add_u64 v[84:85], v[82:83], 0, s[38:39]
	v_lshl_add_u64 v[90:91], v[200:201], 0, v[90:91]
	v_cndmask_b32_e32 v85, v91, v85, vcc
	v_cndmask_b32_e32 v84, v90, v84, vcc
	global_load_dwordx4 v[142:145], v[82:83], off offset:16
	global_load_dwordx4 v[146:149], v[82:83], off
	global_load_dwordx4 v[110:113], v[84:85], off offset:16
	global_load_dwordx4 v[126:129], v[84:85], off
	v_min_i32_e32 v82, 0x187, v92
	v_ashrrev_i32_e32 v83, 31, v82
	v_lshl_add_u64 v[82:83], v[82:83], 2, s[40:41]
	global_load_dword v232, v[82:83], off
	v_mov_b32_e32 v82, v15
	v_mov_b32_e32 v15, v17
	v_mov_b32_e32 v83, v16
	v_pk_mul_f32 v[14:15], v[212:213], v[14:15]
	v_pk_mul_f32 v[12:13], v[204:205], v[12:13]
	v_pk_mul_f32 v[10:11], v[202:203], v[10:11]
	v_pk_fma_f32 v[14:15], v[210:211], v[82:83], v[14:15]
	v_mov_b32_e32 v16, v12
	v_mov_b32_e32 v17, v10
	v_mov_b32_e32 v10, v13
	v_pk_add_f32 v[10:11], v[16:17], v[10:11]
	v_add_f32_e32 v12, v14, v15
	v_add_f32_e32 v11, v11, v12
	v_add_f32_e32 v10, v10, v11
	v_mov_b32_e32 v11, v24
	v_pk_mul_f32 v[14:15], v[202:203], v[18:19]
	v_add_f32_dpp v10, v10, v10 quad_perm:[1,0,3,2] row_mask:0xf bank_mask:0xf bound_ctrl:1
	v_mov_b32_e32 v17, v14
	v_subrev_u32_e32 v18, 24, v223
	v_mov_b32_e32 v18, v250
	v_add_f32_dpp v236, v10, v10 quad_perm:[2,3,0,1] row_mask:0xf bank_mask:0xf bound_ctrl:1
	v_mov_b32_e32 v10, v23
	v_mov_b32_e32 v23, v25
	v_pk_mul_f32 v[12:13], v[212:213], v[22:23]
	v_cmp_lt_i32_e32 vcc, s19, v18
	v_pk_fma_f32 v[10:11], v[210:211], v[10:11], v[12:13]
	v_pk_mul_f32 v[12:13], v[204:205], v[20:21]
	v_add_f32_e32 v10, v10, v11
	v_mov_b32_e32 v16, v12
	v_mov_b32_e32 v14, v13
	v_pk_add_f32 v[12:13], v[16:17], v[14:15]
	v_mov_b32_e32 v11, v32
	v_add_f32_e32 v10, v13, v10
	v_add_f32_e32 v10, v12, v10
	v_pk_mul_f32 v[14:15], v[202:203], v[26:27]
	v_mov_b32_e32 v237, 0
	v_add_f32_dpp v10, v10, v10 quad_perm:[1,0,3,2] row_mask:0xf bank_mask:0xf bound_ctrl:1
	v_mov_b32_e32 v17, v14
	v_mov_b32_e32 v239, 0
	v_add_f32_dpp v238, v10, v10 quad_perm:[2,3,0,1] row_mask:0xf bank_mask:0xf bound_ctrl:1
	v_mov_b32_e32 v10, v31
	v_mov_b32_e32 v31, v33
	v_pk_mul_f32 v[12:13], v[212:213], v[30:31]
	v_mov_b32_e32 v241, 0
	v_pk_fma_f32 v[10:11], v[210:211], v[10:11], v[12:13]
	v_pk_mul_f32 v[12:13], v[204:205], v[28:29]
	v_add_f32_e32 v10, v10, v11
	v_mov_b32_e32 v16, v12
	v_mov_b32_e32 v14, v13
	v_pk_add_f32 v[12:13], v[16:17], v[14:15]
	s_waitcnt vmcnt(23)
	v_mov_b32_e32 v11, v76
	v_add_f32_e32 v10, v13, v10
	v_add_f32_e32 v10, v12, v10
	v_pk_mul_f32 v[14:15], v[202:203], v[70:71]
	v_mov_b32_dpp v237, v236 row_half_mirror row_mask:0xf bank_mask:0xf
	v_add_f32_dpp v10, v10, v10 quad_perm:[1,0,3,2] row_mask:0xf bank_mask:0xf bound_ctrl:1
	v_mov_b32_e32 v17, v14
	v_mov_b32_dpp v239, v238 row_half_mirror row_mask:0xf bank_mask:0xf
	v_add_f32_dpp v240, v10, v10 quad_perm:[2,3,0,1] row_mask:0xf bank_mask:0xf bound_ctrl:1
	v_mov_b32_e32 v10, v75
	v_mov_b32_e32 v75, v77
	v_pk_mul_f32 v[12:13], v[212:213], v[74:75]
	v_mov_b32_e32 v77, 0
	v_pk_fma_f32 v[10:11], v[210:211], v[10:11], v[12:13]
	v_pk_mul_f32 v[12:13], v[204:205], v[72:73]
	v_add_f32_e32 v10, v10, v11
	v_mov_b32_e32 v16, v12
	v_mov_b32_e32 v14, v13
	v_pk_add_f32 v[12:13], v[16:17], v[14:15]
	v_cndmask_b32_e64 v11, 0, 1, vcc
	v_add_f32_e32 v10, v13, v10
	v_add_f32_e32 v10, v12, v10
	v_cmp_gt_i32_e32 vcc, s24, v18
	v_mov_b32_dpp v241, v240 row_half_mirror row_mask:0xf bank_mask:0xf
	v_add_f32_dpp v10, v10, v10 quad_perm:[1,0,3,2] row_mask:0xf bank_mask:0xf bound_ctrl:1
	v_cndmask_b32_e32 v11, 2, v11, vcc
	v_mul_i32_i24_e32 v12, 0xffffff7f, v11
	v_add_f32_dpp v76, v10, v10 quad_perm:[2,3,0,1] row_mask:0xf bank_mask:0xf bound_ctrl:1
	v_min_i32_e32 v10, 0x182, v18
	v_lshlrev_b32_e32 v11, 1, v11
	v_add_lshl_u32 v10, v12, v10, v11
	v_sub_u32_e32 v156, s18, v10
	v_mov_b32_dpp v77, v76 row_half_mirror row_mask:0xf bank_mask:0xf
	v_cmp_lt_i32_e32 vcc, s25, v156
	v_cmp_gt_i32_e64 s[0:1], s17, v156
	s_and_saveexec_b64 s[14:15], s[0:1]
	s_xor_b64 s[0:1], exec, s[14:15]
	v_ashrrev_i32_e32 v11, 31, v156
	v_mov_b32_e32 v10, v156
	v_lshlrev_b64 v[10:11], 11, v[10:11]
	v_lshl_add_u64 v[14:15], v[194:195], 0, v[10:11]
	s_andn2_saveexec_b64 s[0:1], s[0:1]
	v_add_u32_e32 v10, 0xfffff800, v156
	v_mad_u64_u32 v[14:15], s[14:15], v10, s26, v[198:199]
	v_lshlrev_b64 v[10:11], 11, v[156:157]
	s_or_b64 exec, exec, s[0:1]
	v_lshl_add_u64 v[12:13], v[14:15], 0, s[38:39]
	v_lshl_add_u64 v[10:11], v[200:201], 0, v[10:11]
	v_min_i32_e32 v18, 0x187, v18
	v_cndmask_b32_e32 v21, v11, v13, vcc
	v_cndmask_b32_e32 v20, v10, v12, vcc
	global_load_dwordx4 v[10:13], v[14:15], off offset:16
	s_nop 0
	global_load_dwordx4 v[14:17], v[14:15], off
	s_nop 0
	global_load_dwordx4 v[90:93], v[20:21], off offset:16
	global_load_dwordx4 v[150:153], v[20:21], off
	v_ashrrev_i32_e32 v19, 31, v18
	v_lshl_add_u64 v[18:19], v[18:19], 2, s[40:41]
	global_load_dword v233, v[18:19], off
	v_add_u32_e32 v26, -16, v223
	v_mov_b32_e32 v26, v251
	v_cmp_lt_i32_e32 vcc, s19, v26
	v_min_i32_e32 v18, 0x182, v26
	s_nop 0
	v_cndmask_b32_e64 v19, 0, 1, vcc
	v_cmp_gt_i32_e32 vcc, s24, v26
	s_nop 1
	v_cndmask_b32_e32 v19, 2, v19, vcc
	v_mul_i32_i24_e32 v20, 0xffffff7f, v19
	v_lshlrev_b32_e32 v19, 1, v19
	v_add_lshl_u32 v18, v20, v18, v19
	v_sub_u32_e32 v18, s18, v18
	v_cmp_lt_i32_e32 vcc, s25, v18
	v_cmp_gt_i32_e64 s[0:1], s17, v18
	s_and_saveexec_b64 s[14:15], s[0:1]
	s_xor_b64 s[0:1], exec, s[14:15]
	v_ashrrev_i32_e32 v19, 31, v18
	v_lshlrev_b64 v[20:21], 11, v[18:19]
	v_lshl_add_u64 v[22:23], v[194:195], 0, v[20:21]
	s_andn2_saveexec_b64 s[0:1], s[0:1]
	v_add_u32_e32 v19, 0xfffff800, v18
	v_mad_u64_u32 v[22:23], s[14:15], v19, s26, v[198:199]
	v_mov_b32_e32 v19, v157
	v_lshlrev_b64 v[20:21], 11, v[18:19]
	s_or_b64 exec, exec, s[0:1]
	v_lshl_add_u64 v[18:19], v[22:23], 0, s[38:39]
	v_lshl_add_u64 v[20:21], v[200:201], 0, v[20:21]
	v_min_i32_e32 v26, 0x187, v26
	v_cndmask_b32_e32 v29, v21, v19, vcc
	v_cndmask_b32_e32 v28, v20, v18, vcc
	global_load_dwordx4 v[18:21], v[22:23], off offset:16
	s_nop 0
	global_load_dwordx4 v[22:25], v[22:23], off
	s_nop 0
	global_load_dwordx4 v[82:85], v[28:29], off offset:16
	global_load_dwordx4 v[98:101], v[28:29], off
	v_ashrrev_i32_e32 v27, 31, v26
	v_lshl_add_u64 v[26:27], v[26:27], 2, s[40:41]
	global_load_dword v234, v[26:27], off
	v_add_u32_e32 v70, -8, v223
	v_mov_b32_e32 v70, v252
	v_cmp_lt_i32_e32 vcc, s19, v70
	v_min_i32_e32 v26, 0x182, v70
	s_nop 0
	v_cndmask_b32_e64 v27, 0, 1, vcc
	v_cmp_gt_i32_e32 vcc, s24, v70
	s_nop 1
	v_cndmask_b32_e32 v27, 2, v27, vcc
	v_mul_i32_i24_e32 v28, 0xffffff7f, v27
	v_lshlrev_b32_e32 v27, 1, v27
	v_add_lshl_u32 v26, v28, v26, v27
	v_sub_u32_e32 v26, s18, v26
	v_cmp_lt_i32_e32 vcc, s25, v26
	v_cmp_gt_i32_e64 s[0:1], s17, v26
	s_and_saveexec_b64 s[14:15], s[0:1]
	s_xor_b64 s[0:1], exec, s[14:15]
	v_ashrrev_i32_e32 v27, 31, v26
	v_lshlrev_b64 v[28:29], 11, v[26:27]
	v_lshl_add_u64 v[30:31], v[194:195], 0, v[28:29]
	s_andn2_saveexec_b64 s[0:1], s[0:1]
	v_add_u32_e32 v27, 0xfffff800, v26
	v_mad_u64_u32 v[30:31], s[14:15], v27, s26, v[198:199]
	v_mov_b32_e32 v27, v157
	v_lshlrev_b64 v[28:29], 11, v[26:27]
	s_or_b64 exec, exec, s[0:1]
	v_lshl_add_u64 v[26:27], v[30:31], 0, s[38:39]
	v_lshl_add_u64 v[28:29], v[200:201], 0, v[28:29]
	v_min_i32_e32 v70, 0x187, v70
	v_cndmask_b32_e32 v73, v29, v27, vcc
	v_cndmask_b32_e32 v72, v28, v26, vcc
	global_load_dwordx4 v[26:29], v[30:31], off offset:16
	s_nop 0
	global_load_dwordx4 v[30:33], v[30:31], off
	s_nop 0
	global_load_dwordx4 v[106:109], v[72:73], off offset:16
	global_load_dwordx4 v[130:133], v[72:73], off
	v_ashrrev_i32_e32 v71, 31, v70
	v_lshl_add_u64 v[70:71], v[70:71], 2, s[40:41]
	global_load_dword v235, v[70:71], off
	v_mov_b32_e32 v254, v253
	v_cmp_lt_i32_e32 vcc, s19, v254
	v_min_i32_e32 v70, 0x182, v254
	s_nop 0
	v_cndmask_b32_e64 v71, 0, 1, vcc
	v_cmp_gt_i32_e32 vcc, s24, v254
	s_nop 1
	v_cndmask_b32_e32 v71, 2, v71, vcc
	v_mul_i32_i24_e32 v72, 0xffffff7f, v71
	v_lshlrev_b32_e32 v71, 1, v71
	v_add_lshl_u32 v70, v72, v70, v71
	v_sub_u32_e32 v72, s18, v70
	v_cmp_lt_i32_e32 vcc, s25, v72
	v_cmp_gt_i32_e64 s[0:1], s17, v72
	s_and_saveexec_b64 s[14:15], s[0:1]
	s_xor_b64 s[0:1], exec, s[14:15]
	v_ashrrev_i32_e32 v73, 31, v72
	v_lshlrev_b64 v[70:71], 11, v[72:73]
	v_lshl_add_u64 v[74:75], v[194:195], 0, v[70:71]
	s_andn2_saveexec_b64 s[0:1], s[0:1]
	v_add_u32_e32 v70, 0xfffff800, v72
	v_mov_b32_e32 v73, v157
	v_mad_u64_u32 v[74:75], s[14:15], v70, s26, v[198:199]
	v_lshlrev_b64 v[70:71], 11, v[72:73]
	s_or_b64 exec, exec, s[0:1]
	v_add_f32_e32 v72, v236, v237
	v_add_f32_e32 v73, v228, v72
	v_max_f32_e32 v72, v225, v225
	v_max_f32_e32 v156, v72, v73
	v_sub_f32_e32 v73, v73, v156
	v_mul_f32_e32 v73, 0x3fb8aa3b, v73
	v_exp_f32_e32 v228, v73
	v_add_f32_e32 v73, v238, v239
	v_add_f32_e32 v73, v227, v73
	v_sub_f32_e32 v72, v225, v156
	v_max_f32_e32 v225, v156, v73
	v_sub_f32_e32 v73, v73, v225
	v_mul_f32_e32 v73, 0x3fb8aa3b, v73
	v_sub_f32_e32 v156, v156, v225
	v_exp_f32_e32 v238, v73
	v_add_f32_e32 v73, v240, v241
	v_mul_f32_e32 v156, 0x3fb8aa3b, v156
	v_add_f32_e32 v73, v226, v73
	v_mul_f32_e32 v72, 0x3fb8aa3b, v72
	v_exp_f32_e32 v236, v156
	v_max_f32_e32 v156, v225, v73
	v_exp_f32_e32 v72, v72
	v_sub_f32_e32 v225, v225, v156
	v_sub_f32_e32 v73, v73, v156
	v_mul_f32_e32 v225, 0x3fb8aa3b, v225
	v_mul_f32_e32 v73, 0x3fb8aa3b, v73
	v_exp_f32_e32 v226, v225
	v_exp_f32_e32 v240, v73
	v_fma_f32 v73, v224, v72, v228
	v_fma_f32 v73, v73, v236, v238
	s_waitcnt vmcnt(30)
	v_pk_mul_f32 v[42:43], v[42:43], v[228:229] op_sel_hi:[1,0]
	v_fma_f32 v225, v73, v226, v240
	v_add_f32_e32 v73, v76, v77
	v_add_f32_e32 v73, v222, v73
	v_max_f32_e32 v227, v156, v73
	v_sub_f32_e32 v73, v73, v227
	v_sub_f32_e32 v76, v156, v227
	v_mul_f32_e32 v73, 0x3fb8aa3b, v73
	v_mul_f32_e32 v76, 0x3fb8aa3b, v76
	v_exp_f32_e32 v156, v73
	v_exp_f32_e32 v224, v76
	v_pk_fma_f32 v[42:43], v[220:221], v[72:73], v[42:43] op_sel_hi:[1,0,1]
	v_pk_mul_f32 v[50:51], v[50:51], v[238:239] op_sel_hi:[1,0]
	v_pk_mul_f32 v[6:7], v[6:7], v[156:157] op_sel_hi:[1,0]
	v_pk_fma_f32 v[42:43], v[42:43], v[236:237], v[50:51] op_sel_hi:[1,0,1]
	v_pk_mul_f32 v[50:51], v[58:59], v[240:241] op_sel_hi:[1,0]
	v_pk_mul_f32 v[8:9], v[8:9], v[156:157] op_sel_hi:[1,0]
	v_pk_fma_f32 v[42:43], v[42:43], v[226:227], v[50:51] op_sel_hi:[1,0,1]
	v_pk_mul_f32 v[2:3], v[2:3], v[156:157] op_sel_hi:[1,0]
	v_pk_fma_f32 v[42:43], v[42:43], v[224:225], v[6:7] op_sel_hi:[1,0,1]
	v_pk_mul_f32 v[6:7], v[44:45], v[228:229] op_sel_hi:[1,0]
	v_pk_mul_f32 v[44:45], v[52:53], v[238:239] op_sel_hi:[1,0]
	v_pk_fma_f32 v[6:7], v[218:219], v[72:73], v[6:7] op_sel_hi:[1,0,1]
	v_pk_mul_f32 v[4:5], v[4:5], v[156:157] op_sel_hi:[1,0]
	v_pk_fma_f32 v[6:7], v[6:7], v[236:237], v[44:45] op_sel_hi:[1,0,1]
	v_pk_mul_f32 v[44:45], v[60:61], v[240:241] op_sel_hi:[1,0]
	v_fmac_f32_e32 v156, v225, v224
	v_pk_fma_f32 v[6:7], v[6:7], v[226:227], v[44:45] op_sel_hi:[1,0,1]
; __device__ __forceinline__ void p_attn_sample(const float* P, const float* ck, const float* cv, const float* relb, bf16* heads, const float* sbt, unsigned* qctr, volatile LAS unsigned* slot, int wave, int lane_in) {
;     ...
;         SLOADB(ak0, ak1, av0, av1, ab, 0)
	s_add_i32 s3, s3, 8
	v_pk_fma_f32 v[44:45], v[6:7], v[224:225], v[8:9] op_sel_hi:[1,0,1]
	v_pk_mul_f32 v[6:7], v[34:35], v[228:229] op_sel_hi:[1,0]
	v_pk_mul_f32 v[8:9], v[38:39], v[238:239] op_sel_hi:[1,0]
	v_pk_fma_f32 v[6:7], v[214:215], v[72:73], v[6:7] op_sel_hi:[1,0,1]
	v_min_i32_e32 v38, 0x187, v254
	v_pk_fma_f32 v[6:7], v[6:7], v[236:237], v[8:9] op_sel_hi:[1,0,1]
	v_pk_mul_f32 v[8:9], v[46:47], v[240:241] op_sel_hi:[1,0]
	v_ashrrev_i32_e32 v39, 31, v38
	v_pk_fma_f32 v[6:7], v[6:7], v[226:227], v[8:9] op_sel_hi:[1,0,1]
	v_lshl_add_u64 v[38:39], v[38:39], 2, s[40:41]
	v_pk_fma_f32 v[34:35], v[6:7], v[224:225], v[2:3] op_sel_hi:[1,0,1]
	v_pk_mul_f32 v[2:3], v[36:37], v[228:229] op_sel_hi:[1,0]
	v_pk_mul_f32 v[6:7], v[40:41], v[238:239] op_sel_hi:[1,0]
	v_pk_fma_f32 v[2:3], v[216:217], v[72:73], v[2:3] op_sel_hi:[1,0,1]
	v_pk_mul_f32 v[40:41], v[206:207], v[114:115]
	v_pk_fma_f32 v[2:3], v[2:3], v[236:237], v[6:7] op_sel_hi:[1,0,1]
	v_pk_mul_f32 v[6:7], v[48:49], v[240:241] op_sel_hi:[1,0]
	s_cmp_gt_u32 s3, 39
	v_pk_fma_f32 v[2:3], v[2:3], v[226:227], v[6:7] op_sel_hi:[1,0,1]
	v_add_u32_e32 v223, 64, v223
	v_pk_fma_f32 v[36:37], v[2:3], v[224:225], v[4:5] op_sel_hi:[1,0,1]
	v_lshl_add_u64 v[2:3], v[74:75], 0, s[38:39]
	v_lshl_add_u64 v[4:5], v[200:201], 0, v[70:71]
	v_cndmask_b32_e32 v7, v5, v3, vcc
	v_cndmask_b32_e32 v6, v4, v2, vcc
	global_load_dwordx4 v[70:73], v[74:75], off offset:16
	s_nop 0
	global_load_dwordx4 v[74:77], v[74:75], off
	s_nop 0
	global_load_dwordx4 v[2:5], v[6:7], off offset:16
	s_nop 0
	global_load_dwordx4 v[6:9], v[6:7], off
	s_nop 0
	global_load_dword v222, v[38:39], off
	v_pk_mul_f32 v[38:39], v[208:209], v[116:117]
	s_nop 0
	v_pk_mov_b32 v[46:47], v[40:41], v[38:39] op_sel:[1,0]
	v_mov_b32_e32 v41, v39
	v_pk_add_f32 v[38:39], v[46:47], v[40:41]
	v_pk_mul_f32 v[40:41], v[204:205], v[104:105]
	v_pk_mul_f32 v[46:47], v[202:203], v[102:103]
	v_mov_b32_e32 v48, v40
	v_mov_b32_e32 v49, v46
	v_mov_b32_e32 v46, v41
	v_pk_add_f32 v[40:41], v[48:49], v[46:47]
	v_add_f32_e32 v38, v38, v39
	v_add_f32_e32 v38, v38, v41
	v_add_f32_e32 v38, v40, v38
	s_waitcnt vmcnt(33)
	v_pk_mul_f32 v[46:47], v[208:209], v[124:125]
	v_pk_mul_f32 v[48:49], v[206:207], v[122:123]
	v_add_f32_dpp v38, v38, v38 quad_perm:[1,0,3,2] row_mask:0xf bank_mask:0xf bound_ctrl:1
	v_pk_mov_b32 v[50:51], v[48:49], v[46:47] op_sel:[1,0]
	v_mov_b32_e32 v49, v47
	v_add_f32_dpp v38, v38, v38 quad_perm:[2,3,0,1] row_mask:0xf bank_mask:0xf bound_ctrl:1
	v_pk_add_f32 v[46:47], v[50:51], v[48:49]
	v_pk_mul_f32 v[48:49], v[204:205], v[120:121]
	v_add_f32_dpp v38, v38, v38 row_half_mirror row_mask:0xf bank_mask:0xf bound_ctrl:1
	v_add_f32_e32 v39, v229, v38
	v_max_f32_e32 v41, v227, v39
	v_sub_f32_e32 v39, v39, v41
	v_pk_mul_f32 v[50:51], v[202:203], v[118:119]
	v_mul_f32_e32 v39, 0x3fb8aa3b, v39
	v_mov_b32_e32 v52, v48
	v_mov_b32_e32 v53, v50
	v_mov_b32_e32 v50, v49
	v_exp_f32_e32 v40, v39
	v_pk_add_f32 v[48:49], v[52:53], v[50:51]
	v_add_f32_e32 v39, v46, v47
	v_add_f32_e32 v39, v39, v49
	v_add_f32_e32 v39, v48, v39
	s_waitcnt vmcnt(28)
	v_pk_mul_f32 v[50:51], v[208:209], v[140:141]
	v_pk_mul_f32 v[52:53], v[206:207], v[138:139]
	v_add_f32_dpp v39, v39, v39 quad_perm:[1,0,3,2] row_mask:0xf bank_mask:0xf bound_ctrl:1
	v_pk_mov_b32 v[58:59], v[52:53], v[50:51] op_sel:[1,0]
	v_mov_b32_e32 v53, v51
	v_add_f32_dpp v39, v39, v39 quad_perm:[2,3,0,1] row_mask:0xf bank_mask:0xf bound_ctrl:1
	v_pk_add_f32 v[50:51], v[58:59], v[52:53]
	v_pk_mul_f32 v[52:53], v[204:205], v[136:137]
	v_add_f32_dpp v39, v39, v39 row_half_mirror row_mask:0xf bank_mask:0xf bound_ctrl:1
	v_add_f32_e32 v39, v230, v39
	v_max_f32_e32 v47, v41, v39
	v_sub_f32_e32 v39, v39, v47
	v_pk_mul_f32 v[58:59], v[202:203], v[134:135]
	v_mul_f32_e32 v39, 0x3fb8aa3b, v39
	v_mov_b32_e32 v60, v52
	v_mov_b32_e32 v61, v58
	v_mov_b32_e32 v58, v53
	v_exp_f32_e32 v48, v39
	v_pk_add_f32 v[52:53], v[60:61], v[58:59]
	v_add_f32_e32 v39, v50, v51
	v_add_f32_e32 v39, v39, v53
	v_add_f32_e32 v39, v52, v39
	v_sub_f32_e32 v38, v227, v41
	v_sub_f32_e32 v41, v41, v47
	v_add_f32_dpp v39, v39, v39 quad_perm:[1,0,3,2] row_mask:0xf bank_mask:0xf bound_ctrl:1
	v_mul_f32_e32 v41, 0x3fb8aa3b, v41
	s_waitcnt vmcnt(23)
; __device__ __forceinline__ void p_attn_sample(const float* P, const float* ck, const float* cv, const float* relb, bf16* heads, const float* sbt, unsigned* qctr, volatile LAS unsigned* slot, int wave, int lane_in) {
;     ...
;         SLOADB(ak0, ak1, av0, av1, ab, 0)
; #pragma unroll 1
;         for (int it0 = 0; it0 < 48; it0 += 8) {
;             SLOADB(bk0, bk1, bv0, bv1, bbv, it0 + 4)
;             SPROCB(ak0, ak1, av0, av1, ab)
;             SLOADB(ak0, ak1, av0, av1, ab, it0 + 8)
;             SPROCB(bk0, bk1, bv0, bv1, bbv)
;         }
	v_pk_mul_f32 v[58:59], v[208:209], v[148:149]
	v_add_f32_dpp v39, v39, v39 quad_perm:[2,3,0,1] row_mask:0xf bank_mask:0xf bound_ctrl:1
	v_pk_mul_f32 v[60:61], v[206:207], v[146:147]
	v_exp_f32_e32 v46, v41
	v_add_f32_dpp v39, v39, v39 row_half_mirror row_mask:0xf bank_mask:0xf bound_ctrl:1
	v_add_f32_e32 v39, v231, v39
	v_max_f32_e32 v41, v47, v39
	v_pk_mov_b32 v[102:103], v[60:61], v[58:59] op_sel:[1,0]
	v_mov_b32_e32 v61, v59
	v_sub_f32_e32 v39, v39, v41
	v_pk_add_f32 v[58:59], v[102:103], v[60:61]
	v_pk_mul_f32 v[60:61], v[204:205], v[144:145]
	v_pk_mul_f32 v[102:103], v[202:203], v[142:143]
	v_mul_f32_e32 v39, 0x3fb8aa3b, v39
	v_mov_b32_e32 v104, v60
	v_mov_b32_e32 v105, v102
	v_mov_b32_e32 v102, v61
	v_exp_f32_e32 v52, v39
	v_pk_add_f32 v[60:61], v[104:105], v[102:103]
	v_add_f32_e32 v39, v58, v59
	v_add_f32_e32 v39, v39, v61
	v_add_f32_e32 v39, v60, v39
	v_mul_f32_e32 v38, 0x3fb8aa3b, v38
	v_exp_f32_e32 v38, v38
	v_add_f32_dpp v39, v39, v39 quad_perm:[1,0,3,2] row_mask:0xf bank_mask:0xf bound_ctrl:1
	v_sub_f32_e32 v47, v47, v41
	v_mul_f32_e32 v47, 0x3fb8aa3b, v47
	v_add_f32_dpp v39, v39, v39 quad_perm:[2,3,0,1] row_mask:0xf bank_mask:0xf bound_ctrl:1
	v_exp_f32_e32 v50, v47
	s_nop 0
	v_add_f32_dpp v39, v39, v39 row_half_mirror row_mask:0xf bank_mask:0xf bound_ctrl:1
	s_waitcnt vmcnt(20)
	v_add_f32_e32 v39, v232, v39
	v_max_f32_e32 v225, v41, v39
	v_sub_f32_e32 v39, v39, v225
	v_mul_f32_e32 v39, 0x3fb8aa3b, v39
	v_sub_f32_e32 v41, v41, v225
	v_exp_f32_e32 v60, v39
	v_fma_f32 v39, v156, v38, v40
	v_mul_f32_e32 v41, 0x3fb8aa3b, v41
	v_fma_f32 v39, v39, v46, v48
	v_exp_f32_e32 v58, v41
	v_fma_f32 v39, v39, v50, v52
	v_pk_mul_f32 v[62:63], v[62:63], v[40:41] op_sel_hi:[1,0]
	v_fma_f32 v224, v39, v58, v60
	v_pk_fma_f32 v[42:43], v[42:43], v[38:39], v[62:63] op_sel_hi:[1,0,1]
	v_pk_mul_f32 v[62:63], v[78:79], v[48:49] op_sel_hi:[1,0]
	s_nop 0
	v_pk_fma_f32 v[42:43], v[42:43], v[46:47], v[62:63] op_sel_hi:[1,0,1]
	v_pk_mul_f32 v[62:63], v[94:95], v[52:53] op_sel_hi:[1,0]
	s_nop 0
	v_pk_fma_f32 v[42:43], v[42:43], v[50:51], v[62:63] op_sel_hi:[1,0,1]
	v_pk_mul_f32 v[62:63], v[126:127], v[60:61] op_sel_hi:[1,0]
	s_nop 0
	v_pk_fma_f32 v[220:221], v[42:43], v[58:59], v[62:63] op_sel_hi:[1,0,1]
	v_pk_mul_f32 v[42:43], v[64:65], v[40:41] op_sel_hi:[1,0]
	s_nop 0
	v_pk_fma_f32 v[42:43], v[44:45], v[38:39], v[42:43] op_sel_hi:[1,0,1]
	v_pk_mul_f32 v[44:45], v[80:81], v[48:49] op_sel_hi:[1,0]
	s_nop 0
	v_pk_fma_f32 v[42:43], v[42:43], v[46:47], v[44:45] op_sel_hi:[1,0,1]
	v_pk_mul_f32 v[44:45], v[96:97], v[52:53] op_sel_hi:[1,0]
	s_nop 0
	v_pk_fma_f32 v[42:43], v[42:43], v[50:51], v[44:45] op_sel_hi:[1,0,1]
	v_pk_mul_f32 v[44:45], v[128:129], v[60:61] op_sel_hi:[1,0]
	s_nop 0
	v_pk_fma_f32 v[218:219], v[42:43], v[58:59], v[44:45] op_sel_hi:[1,0,1]
	v_pk_mul_f32 v[42:43], v[54:55], v[40:41] op_sel_hi:[1,0]
	s_nop 0
	v_pk_fma_f32 v[34:35], v[34:35], v[38:39], v[42:43] op_sel_hi:[1,0,1]
	v_pk_mul_f32 v[42:43], v[66:67], v[48:49] op_sel_hi:[1,0]
	s_nop 0
	v_pk_fma_f32 v[34:35], v[34:35], v[46:47], v[42:43] op_sel_hi:[1,0,1]
	v_pk_mul_f32 v[42:43], v[86:87], v[52:53] op_sel_hi:[1,0]
	s_nop 0
	v_pk_fma_f32 v[34:35], v[34:35], v[50:51], v[42:43] op_sel_hi:[1,0,1]
	v_pk_mul_f32 v[42:43], v[110:111], v[60:61] op_sel_hi:[1,0]
	s_nop 0
	v_pk_fma_f32 v[214:215], v[34:35], v[58:59], v[42:43] op_sel_hi:[1,0,1]
	v_pk_mul_f32 v[34:35], v[56:57], v[40:41] op_sel_hi:[1,0]
	s_nop 0
	v_pk_fma_f32 v[34:35], v[36:37], v[38:39], v[34:35] op_sel_hi:[1,0,1]
	v_pk_mul_f32 v[36:37], v[68:69], v[48:49] op_sel_hi:[1,0]
	s_nop 0
	v_pk_fma_f32 v[34:35], v[34:35], v[46:47], v[36:37] op_sel_hi:[1,0,1]
	v_pk_mul_f32 v[36:37], v[88:89], v[52:53] op_sel_hi:[1,0]
	s_nop 0
	v_pk_fma_f32 v[34:35], v[34:35], v[50:51], v[36:37] op_sel_hi:[1,0,1]
	v_pk_mul_f32 v[36:37], v[112:113], v[60:61] op_sel_hi:[1,0]
	s_nop 0
	v_pk_fma_f32 v[216:217], v[34:35], v[58:59], v[36:37] op_sel_hi:[1,0,1]
	s_cbranch_scc1 .LBB0_1285
	s_waitcnt vmcnt(17)
	v_mov_b64_e32 v[34:35], v[90:91]
	s_waitcnt vmcnt(12)
	v_mov_b64_e32 v[38:39], v[82:83]
	s_waitcnt vmcnt(7)
	v_mov_b64_e32 v[46:47], v[106:107]
	v_mov_b64_e32 v[42:43], v[150:151]
	v_mov_b64_e32 v[50:51], v[98:99]
	s_waitcnt vmcnt(6)
	v_mov_b64_e32 v[58:59], v[130:131]
	v_mov_b64_e32 v[36:37], v[92:93]
	v_mov_b64_e32 v[40:41], v[84:85]
	v_mov_b64_e32 v[48:49], v[108:109]
	v_mov_b64_e32 v[44:45], v[152:153]
	v_mov_b64_e32 v[52:53], v[100:101]
	v_mov_b64_e32 v[60:61], v[132:133]
	s_waitcnt vmcnt(5)
	v_mov_b32_e32 v226, v235
	v_mov_b32_e32 v227, v234
	v_mov_b32_e32 v228, v233
	s_branch .LBB0_1251

.LBB0_1383:
	v_subrev_u32_e32 v255, 56, v222
	v_min_i32_e32 v255, 0x187, v255
	v_lshl_add_u32 v255, v255, 2, s101
	ds_read_b32 v246, v255
	v_subrev_u32_e32 v255, 48, v222
	v_min_i32_e32 v255, 0x187, v255
	v_lshl_add_u32 v255, v255, 2, s101
	ds_read_b32 v247, v255
	v_subrev_u32_e32 v255, 40, v222
	v_min_i32_e32 v255, 0x187, v255
	v_lshl_add_u32 v255, v255, 2, s101
	ds_read_b32 v248, v255
	v_subrev_u32_e32 v255, 32, v222
	v_min_i32_e32 v255, 0x187, v255
	v_lshl_add_u32 v255, v255, 2, s101
	ds_read_b32 v249, v255
	v_subrev_u32_e32 v255, 24, v222
	v_min_i32_e32 v255, 0x187, v255
	v_lshl_add_u32 v255, v255, 2, s101
	ds_read_b32 v250, v255
	v_subrev_u32_e32 v255, 16, v222
	v_min_i32_e32 v255, 0x187, v255
	v_lshl_add_u32 v255, v255, 2, s101
	ds_read_b32 v251, v255
	v_subrev_u32_e32 v255, 8, v222
	v_min_i32_e32 v255, 0x187, v255
	v_lshl_add_u32 v255, v255, 2, s101
	ds_read_b32 v252, v255
	v_min_i32_e32 v255, 0x187, v222
	v_lshl_add_u32 v255, v255, 2, s101
	ds_read_b32 v253, v255
	s_waitcnt lgkmcnt(0)
	v_subrev_u32_e32 v66, 56, v222
	v_mov_b32_e32 v66, v246
	v_cmp_lt_i32_e32 vcc, s19, v66
	v_min_i32_e32 v54, 0x182, v66
	s_nop 0
	v_cndmask_b32_e64 v55, 0, 1, vcc
	v_cmp_gt_i32_e32 vcc, s23, v66
	s_nop 1
	v_cndmask_b32_e32 v55, 2, v55, vcc
	v_mul_i32_i24_e32 v56, 0xffffff7f, v55
	v_lshlrev_b32_e32 v55, 1, v55
	v_add_lshl_u32 v54, v56, v54, v55
	v_sub_u32_e32 v156, s18, v54
	v_cmp_lt_i32_e32 vcc, s26, v156
	v_cmp_gt_i32_e64 s[0:1], s17, v156
	s_and_saveexec_b64 s[14:15], s[0:1]
	s_xor_b64 s[0:1], exec, s[14:15]
	v_ashrrev_i32_e32 v55, 31, v156
	v_mov_b32_e32 v54, v156
	v_lshlrev_b64 v[56:57], 11, v[54:55]
	v_lshl_add_u64 v[54:55], v[194:195], 0, v[56:57]
	s_andn2_saveexec_b64 s[0:1], s[0:1]
	v_add_u32_e32 v54, 0xfffff800, v156
	v_mad_u64_u32 v[54:55], s[14:15], v54, s27, v[196:197]
	v_lshlrev_b64 v[56:57], 11, v[156:157]
	s_or_b64 exec, exec, s[0:1]
	v_lshl_add_u64 v[62:63], v[54:55], 0, s[28:29]
	v_lshl_add_u64 v[56:57], v[198:199], 0, v[56:57]
	v_cndmask_b32_e32 v63, v57, v63, vcc
	v_cndmask_b32_e32 v62, v56, v62, vcc
	v_min_i32_e32 v66, 0x187, v66
	global_load_dwordx4 v[102:105], v[54:55], off offset:16
	global_load_dwordx4 v[114:117], v[54:55], off
	s_nop 0
	global_load_dwordx4 v[54:57], v[62:63], off offset:16
	s_nop 0
	global_load_dwordx4 v[62:65], v[62:63], off
	v_ashrrev_i32_e32 v67, 31, v66
	v_lshl_add_u64 v[66:67], v[66:67], 2, s[30:31]
	global_load_dword v228, v[66:67], off
	v_subrev_u32_e32 v82, 48, v222
	v_mov_b32_e32 v82, v247
	v_cmp_lt_i32_e32 vcc, s19, v82
	v_min_i32_e32 v66, 0x182, v82
	s_nop 0
	v_cndmask_b32_e64 v67, 0, 1, vcc
	v_cmp_gt_i32_e32 vcc, s23, v82
	s_nop 1
	v_cndmask_b32_e32 v67, 2, v67, vcc
	v_mul_i32_i24_e32 v68, 0xffffff7f, v67
	v_lshlrev_b32_e32 v67, 1, v67
	v_add_lshl_u32 v66, v68, v66, v67
	v_sub_u32_e32 v68, s18, v66
	v_cmp_lt_i32_e32 vcc, s26, v68
	v_cmp_gt_i32_e64 s[0:1], s17, v68
	s_and_saveexec_b64 s[14:15], s[0:1]
	s_xor_b64 s[0:1], exec, s[14:15]
	v_ashrrev_i32_e32 v69, 31, v68
	v_lshlrev_b64 v[78:79], 11, v[68:69]
	v_lshl_add_u64 v[66:67], v[194:195], 0, v[78:79]
	s_andn2_saveexec_b64 s[0:1], s[0:1]
	v_add_u32_e32 v66, 0xfffff800, v68
	v_mov_b32_e32 v69, v157
	v_mad_u64_u32 v[66:67], s[14:15], v66, s27, v[196:197]
	v_lshlrev_b64 v[78:79], 11, v[68:69]
	s_or_b64 exec, exec, s[0:1]
	v_lshl_add_u64 v[68:69], v[66:67], 0, s[28:29]
	v_lshl_add_u64 v[78:79], v[198:199], 0, v[78:79]
	v_cndmask_b32_e32 v79, v79, v69, vcc
	v_cndmask_b32_e32 v78, v78, v68, vcc
	v_min_i32_e32 v82, 0x187, v82
	global_load_dwordx4 v[118:121], v[66:67], off offset:16
	global_load_dwordx4 v[122:125], v[66:67], off
	s_nop 0
	global_load_dwordx4 v[66:69], v[78:79], off offset:16
	s_nop 0
	global_load_dwordx4 v[78:81], v[78:79], off
	v_ashrrev_i32_e32 v83, 31, v82
	v_lshl_add_u64 v[82:83], v[82:83], 2, s[30:31]
	global_load_dword v229, v[82:83], off
	v_subrev_u32_e32 v90, 40, v222
	v_mov_b32_e32 v90, v248
	v_cmp_lt_i32_e32 vcc, s19, v90
	v_min_i32_e32 v82, 0x182, v90
	s_nop 0
	v_cndmask_b32_e64 v83, 0, 1, vcc
	v_cmp_gt_i32_e32 vcc, s23, v90
	s_nop 1
	v_cndmask_b32_e32 v83, 2, v83, vcc
	v_mul_i32_i24_e32 v84, 0xffffff7f, v83
	v_lshlrev_b32_e32 v83, 1, v83
	v_add_lshl_u32 v82, v84, v82, v83
	v_sub_u32_e32 v84, s18, v82
	v_cmp_lt_i32_e32 vcc, s26, v84
	v_cmp_gt_i32_e64 s[0:1], s17, v84
	s_and_saveexec_b64 s[14:15], s[0:1]
	s_xor_b64 s[0:1], exec, s[14:15]
	v_ashrrev_i32_e32 v85, 31, v84
	v_lshlrev_b64 v[86:87], 11, v[84:85]
	v_lshl_add_u64 v[82:83], v[194:195], 0, v[86:87]
	s_andn2_saveexec_b64 s[0:1], s[0:1]
	v_add_u32_e32 v82, 0xfffff800, v84
	v_mov_b32_e32 v85, v157
	v_mad_u64_u32 v[82:83], s[14:15], v82, s27, v[196:197]
	v_lshlrev_b64 v[86:87], 11, v[84:85]
	s_or_b64 exec, exec, s[0:1]
	v_lshl_add_u64 v[84:85], v[82:83], 0, s[28:29]
	v_lshl_add_u64 v[86:87], v[198:199], 0, v[86:87]
	v_cndmask_b32_e32 v85, v87, v85, vcc
	v_cndmask_b32_e32 v84, v86, v84, vcc
	global_load_dwordx4 v[134:137], v[82:83], off offset:16
	global_load_dwordx4 v[138:141], v[82:83], off
	global_load_dwordx4 v[86:89], v[84:85], off offset:16
	global_load_dwordx4 v[94:97], v[84:85], off
	v_min_i32_e32 v82, 0x187, v90
	v_ashrrev_i32_e32 v83, 31, v82
	v_lshl_add_u64 v[82:83], v[82:83], 2, s[30:31]
	global_load_dword v230, v[82:83], off
	v_subrev_u32_e32 v92, 32, v222
	v_mov_b32_e32 v92, v249
	v_cmp_lt_i32_e32 vcc, s19, v92
	v_min_i32_e32 v82, 0x182, v92
	s_nop 0
	v_cndmask_b32_e64 v83, 0, 1, vcc
	v_cmp_gt_i32_e32 vcc, s23, v92
	s_nop 1
	v_cndmask_b32_e32 v83, 2, v83, vcc
	v_mul_i32_i24_e32 v84, 0xffffff7f, v83
	v_lshlrev_b32_e32 v83, 1, v83
	v_add_lshl_u32 v82, v84, v82, v83
	v_sub_u32_e32 v84, s18, v82
	v_cmp_lt_i32_e32 vcc, s26, v84
	v_cmp_gt_i32_e64 s[0:1], s17, v84
	s_and_saveexec_b64 s[14:15], s[0:1]
	s_xor_b64 s[0:1], exec, s[14:15]
	v_ashrrev_i32_e32 v85, 31, v84
	v_lshlrev_b64 v[90:91], 11, v[84:85]
	v_lshl_add_u64 v[82:83], v[194:195], 0, v[90:91]
	s_andn2_saveexec_b64 s[0:1], s[0:1]
	v_add_u32_e32 v82, 0xfffff800, v84
	v_mov_b32_e32 v85, v157
	v_mad_u64_u32 v[82:83], s[14:15], v82, s27, v[196:197]
	v_lshlrev_b64 v[90:91], 11, v[84:85]
	s_or_b64 exec, exec, s[0:1]
	v_lshl_add_u64 v[84:85], v[82:83], 0, s[28:29]
	v_lshl_add_u64 v[90:91], v[198:199], 0, v[90:91]
	v_cndmask_b32_e32 v85, v91, v85, vcc
	v_cndmask_b32_e32 v84, v90, v84, vcc
	global_load_dwordx4 v[142:145], v[82:83], off offset:16
	global_load_dwordx4 v[146:149], v[82:83], off
	global_load_dwordx4 v[110:113], v[84:85], off offset:16
	global_load_dwordx4 v[126:129], v[84:85], off
	v_min_i32_e32 v82, 0x187, v92
	v_ashrrev_i32_e32 v83, 31, v82
	v_lshl_add_u64 v[82:83], v[82:83], 2, s[30:31]
	global_load_dword v231, v[82:83], off
	v_mov_b32_e32 v82, v15
	v_mov_b32_e32 v15, v17
	v_mov_b32_e32 v83, v16
	v_pk_mul_f32 v[14:15], v[210:211], v[14:15]
	v_pk_mul_f32 v[12:13], v[202:203], v[12:13]
	v_pk_mul_f32 v[10:11], v[200:201], v[10:11]
	v_pk_fma_f32 v[14:15], v[208:209], v[82:83], v[14:15]
	v_mov_b32_e32 v16, v12
	v_mov_b32_e32 v17, v10
	v_mov_b32_e32 v10, v13
	v_pk_add_f32 v[10:11], v[16:17], v[10:11]
	v_add_f32_e32 v12, v14, v15
	v_add_f32_e32 v11, v11, v12
	v_add_f32_e32 v10, v10, v11
	v_mov_b32_e32 v11, v24
	v_pk_mul_f32 v[14:15], v[200:201], v[18:19]
	v_add_f32_dpp v10, v10, v10 quad_perm:[1,0,3,2] row_mask:0xf bank_mask:0xf bound_ctrl:1
	v_mov_b32_e32 v17, v14
	v_subrev_u32_e32 v18, 24, v222
	v_mov_b32_e32 v18, v250
	v_add_f32_dpp v235, v10, v10 quad_perm:[2,3,0,1] row_mask:0xf bank_mask:0xf bound_ctrl:1
	v_mov_b32_e32 v10, v23
	v_mov_b32_e32 v23, v25
	v_pk_mul_f32 v[12:13], v[210:211], v[22:23]
	v_cmp_lt_i32_e32 vcc, s19, v18
	v_pk_fma_f32 v[10:11], v[208:209], v[10:11], v[12:13]
	v_pk_mul_f32 v[12:13], v[202:203], v[20:21]
	v_add_f32_e32 v10, v10, v11
	v_mov_b32_e32 v16, v12
	v_mov_b32_e32 v14, v13
	v_pk_add_f32 v[12:13], v[16:17], v[14:15]
	v_mov_b32_e32 v11, v32
	v_add_f32_e32 v10, v13, v10
	v_add_f32_e32 v10, v12, v10
	v_pk_mul_f32 v[14:15], v[200:201], v[26:27]
	v_mov_b32_e32 v236, 0
	v_add_f32_dpp v10, v10, v10 quad_perm:[1,0,3,2] row_mask:0xf bank_mask:0xf bound_ctrl:1
	v_mov_b32_e32 v17, v14
	v_mov_b32_e32 v238, 0
	v_add_f32_dpp v237, v10, v10 quad_perm:[2,3,0,1] row_mask:0xf bank_mask:0xf bound_ctrl:1
	v_mov_b32_e32 v10, v31
	v_mov_b32_e32 v31, v33
	v_pk_mul_f32 v[12:13], v[210:211], v[30:31]
	v_mov_b32_e32 v240, 0
	v_pk_fma_f32 v[10:11], v[208:209], v[10:11], v[12:13]
	v_pk_mul_f32 v[12:13], v[202:203], v[28:29]
	v_add_f32_e32 v10, v10, v11
	v_mov_b32_e32 v16, v12
	v_mov_b32_e32 v14, v13
	v_pk_add_f32 v[12:13], v[16:17], v[14:15]
	s_waitcnt vmcnt(23)
	v_mov_b32_e32 v11, v76
	v_add_f32_e32 v10, v13, v10
	v_add_f32_e32 v10, v12, v10
	v_pk_mul_f32 v[14:15], v[200:201], v[70:71]
	v_mov_b32_dpp v236, v235 row_half_mirror row_mask:0xf bank_mask:0xf
	v_add_f32_dpp v10, v10, v10 quad_perm:[1,0,3,2] row_mask:0xf bank_mask:0xf bound_ctrl:1
	v_mov_b32_e32 v17, v14
	v_mov_b32_dpp v238, v237 row_half_mirror row_mask:0xf bank_mask:0xf
	v_add_f32_dpp v239, v10, v10 quad_perm:[2,3,0,1] row_mask:0xf bank_mask:0xf bound_ctrl:1
	v_mov_b32_e32 v10, v75
	v_mov_b32_e32 v75, v77
	v_pk_mul_f32 v[12:13], v[210:211], v[74:75]
	v_mov_b32_e32 v77, 0
	v_pk_fma_f32 v[10:11], v[208:209], v[10:11], v[12:13]
	v_pk_mul_f32 v[12:13], v[202:203], v[72:73]
	v_add_f32_e32 v10, v10, v11
	v_mov_b32_e32 v16, v12
	v_mov_b32_e32 v14, v13
	v_pk_add_f32 v[12:13], v[16:17], v[14:15]
	v_cndmask_b32_e64 v11, 0, 1, vcc
	v_add_f32_e32 v10, v13, v10
	v_add_f32_e32 v10, v12, v10
	v_cmp_gt_i32_e32 vcc, s23, v18
	v_mov_b32_dpp v240, v239 row_half_mirror row_mask:0xf bank_mask:0xf
	v_add_f32_dpp v10, v10, v10 quad_perm:[1,0,3,2] row_mask:0xf bank_mask:0xf bound_ctrl:1
	v_cndmask_b32_e32 v11, 2, v11, vcc
	v_mul_i32_i24_e32 v12, 0xffffff7f, v11
	v_add_f32_dpp v76, v10, v10 quad_perm:[2,3,0,1] row_mask:0xf bank_mask:0xf bound_ctrl:1
	v_min_i32_e32 v10, 0x182, v18
	v_lshlrev_b32_e32 v11, 1, v11
	v_add_lshl_u32 v10, v12, v10, v11
	v_sub_u32_e32 v156, s18, v10
	v_mov_b32_dpp v77, v76 row_half_mirror row_mask:0xf bank_mask:0xf
	v_cmp_lt_i32_e32 vcc, s26, v156
	v_cmp_gt_i32_e64 s[0:1], s17, v156
	s_and_saveexec_b64 s[14:15], s[0:1]
	s_xor_b64 s[0:1], exec, s[14:15]
	v_ashrrev_i32_e32 v11, 31, v156
	v_mov_b32_e32 v10, v156
	v_lshlrev_b64 v[10:11], 11, v[10:11]
	v_lshl_add_u64 v[14:15], v[194:195], 0, v[10:11]
	s_andn2_saveexec_b64 s[0:1], s[0:1]
	v_add_u32_e32 v10, 0xfffff800, v156
	v_mad_u64_u32 v[14:15], s[14:15], v10, s27, v[196:197]
	v_lshlrev_b64 v[10:11], 11, v[156:157]
	s_or_b64 exec, exec, s[0:1]
	v_lshl_add_u64 v[12:13], v[14:15], 0, s[28:29]
	v_lshl_add_u64 v[10:11], v[198:199], 0, v[10:11]
	v_min_i32_e32 v18, 0x187, v18
	v_cndmask_b32_e32 v21, v11, v13, vcc
	v_cndmask_b32_e32 v20, v10, v12, vcc
	global_load_dwordx4 v[10:13], v[14:15], off offset:16
	s_nop 0
	global_load_dwordx4 v[14:17], v[14:15], off
	s_nop 0
	global_load_dwordx4 v[90:93], v[20:21], off offset:16
	global_load_dwordx4 v[150:153], v[20:21], off
	v_ashrrev_i32_e32 v19, 31, v18
	v_lshl_add_u64 v[18:19], v[18:19], 2, s[30:31]
	global_load_dword v232, v[18:19], off
	v_add_u32_e32 v26, -16, v222
	v_mov_b32_e32 v26, v251
	v_cmp_lt_i32_e32 vcc, s19, v26
	v_min_i32_e32 v18, 0x182, v26
	s_nop 0
	v_cndmask_b32_e64 v19, 0, 1, vcc
	v_cmp_gt_i32_e32 vcc, s23, v26
	s_nop 1
	v_cndmask_b32_e32 v19, 2, v19, vcc
	v_mul_i32_i24_e32 v20, 0xffffff7f, v19
	v_lshlrev_b32_e32 v19, 1, v19
	v_add_lshl_u32 v18, v20, v18, v19
	v_sub_u32_e32 v18, s18, v18
	v_cmp_lt_i32_e32 vcc, s26, v18
	v_cmp_gt_i32_e64 s[0:1], s17, v18
	s_and_saveexec_b64 s[14:15], s[0:1]
	s_xor_b64 s[0:1], exec, s[14:15]
	v_ashrrev_i32_e32 v19, 31, v18
	v_lshlrev_b64 v[20:21], 11, v[18:19]
	v_lshl_add_u64 v[22:23], v[194:195], 0, v[20:21]
	s_andn2_saveexec_b64 s[0:1], s[0:1]
	v_add_u32_e32 v19, 0xfffff800, v18
	v_mad_u64_u32 v[22:23], s[14:15], v19, s27, v[196:197]
	v_mov_b32_e32 v19, v157
	v_lshlrev_b64 v[20:21], 11, v[18:19]
	s_or_b64 exec, exec, s[0:1]
	v_lshl_add_u64 v[18:19], v[22:23], 0, s[28:29]
	v_lshl_add_u64 v[20:21], v[198:199], 0, v[20:21]
	v_min_i32_e32 v26, 0x187, v26
	v_cndmask_b32_e32 v29, v21, v19, vcc
	v_cndmask_b32_e32 v28, v20, v18, vcc
	global_load_dwordx4 v[18:21], v[22:23], off offset:16
	s_nop 0
	global_load_dwordx4 v[22:25], v[22:23], off
	s_nop 0
	global_load_dwordx4 v[82:85], v[28:29], off offset:16
	global_load_dwordx4 v[98:101], v[28:29], off
	v_ashrrev_i32_e32 v27, 31, v26
	v_lshl_add_u64 v[26:27], v[26:27], 2, s[30:31]
	global_load_dword v233, v[26:27], off
	v_add_u32_e32 v70, -8, v222
	v_mov_b32_e32 v70, v252
	v_cmp_lt_i32_e32 vcc, s19, v70
	v_min_i32_e32 v26, 0x182, v70
	s_nop 0
	v_cndmask_b32_e64 v27, 0, 1, vcc
	v_cmp_gt_i32_e32 vcc, s23, v70
	s_nop 1
	v_cndmask_b32_e32 v27, 2, v27, vcc
	v_mul_i32_i24_e32 v28, 0xffffff7f, v27
	v_lshlrev_b32_e32 v27, 1, v27
	v_add_lshl_u32 v26, v28, v26, v27
	v_sub_u32_e32 v26, s18, v26
	v_cmp_lt_i32_e32 vcc, s26, v26
	v_cmp_gt_i32_e64 s[0:1], s17, v26
	s_and_saveexec_b64 s[14:15], s[0:1]
	s_xor_b64 s[0:1], exec, s[14:15]
	v_ashrrev_i32_e32 v27, 31, v26
	v_lshlrev_b64 v[28:29], 11, v[26:27]
	v_lshl_add_u64 v[30:31], v[194:195], 0, v[28:29]
	s_andn2_saveexec_b64 s[0:1], s[0:1]
	v_add_u32_e32 v27, 0xfffff800, v26
	v_mad_u64_u32 v[30:31], s[14:15], v27, s27, v[196:197]
	v_mov_b32_e32 v27, v157
	v_lshlrev_b64 v[28:29], 11, v[26:27]
	s_or_b64 exec, exec, s[0:1]
	v_lshl_add_u64 v[26:27], v[30:31], 0, s[28:29]
	v_lshl_add_u64 v[28:29], v[198:199], 0, v[28:29]
	v_min_i32_e32 v70, 0x187, v70
	v_cndmask_b32_e32 v73, v29, v27, vcc
	v_cndmask_b32_e32 v72, v28, v26, vcc
	global_load_dwordx4 v[26:29], v[30:31], off offset:16
	s_nop 0
	global_load_dwordx4 v[30:33], v[30:31], off
	s_nop 0
	global_load_dwordx4 v[106:109], v[72:73], off offset:16
	global_load_dwordx4 v[130:133], v[72:73], off
	v_ashrrev_i32_e32 v71, 31, v70
	v_lshl_add_u64 v[70:71], v[70:71], 2, s[30:31]
	global_load_dword v234, v[70:71], off
	v_mov_b32_e32 v254, v253
	v_cmp_lt_i32_e32 vcc, s19, v254
	v_min_i32_e32 v70, 0x182, v254
	s_nop 0
	v_cndmask_b32_e64 v71, 0, 1, vcc
	v_cmp_gt_i32_e32 vcc, s23, v254
	s_nop 1
	v_cndmask_b32_e32 v71, 2, v71, vcc
	v_mul_i32_i24_e32 v72, 0xffffff7f, v71
	v_lshlrev_b32_e32 v71, 1, v71
	v_add_lshl_u32 v70, v72, v70, v71
	v_sub_u32_e32 v72, s18, v70
	v_cmp_lt_i32_e32 vcc, s26, v72
	v_cmp_gt_i32_e64 s[0:1], s17, v72
	s_and_saveexec_b64 s[14:15], s[0:1]
	s_xor_b64 s[0:1], exec, s[14:15]
	v_ashrrev_i32_e32 v73, 31, v72
	v_lshlrev_b64 v[70:71], 11, v[72:73]
	v_lshl_add_u64 v[74:75], v[194:195], 0, v[70:71]
	s_andn2_saveexec_b64 s[0:1], s[0:1]
	v_add_u32_e32 v70, 0xfffff800, v72
	v_mov_b32_e32 v73, v157
	v_mad_u64_u32 v[74:75], s[14:15], v70, s27, v[196:197]
	v_lshlrev_b64 v[70:71], 11, v[72:73]
	s_or_b64 exec, exec, s[0:1]
	v_add_f32_e32 v72, v235, v236
	v_add_f32_e32 v73, v227, v72
	v_max_f32_e32 v72, v224, v224
	v_max_f32_e32 v156, v72, v73
	v_sub_f32_e32 v73, v73, v156
	v_mul_f32_e32 v73, 0x3fb8aa3b, v73
	v_sub_f32_e32 v72, v224, v156
	v_exp_f32_e32 v224, v73
	v_add_f32_e32 v73, v237, v238
	v_add_f32_e32 v73, v226, v73
	v_max_f32_e32 v227, v156, v73
	v_sub_f32_e32 v73, v73, v227
	v_mul_f32_e32 v73, 0x3fb8aa3b, v73
	v_sub_f32_e32 v156, v156, v227
	v_exp_f32_e32 v236, v73
	v_add_f32_e32 v73, v239, v240
	v_mul_f32_e32 v156, 0x3fb8aa3b, v156
	v_add_f32_e32 v73, v225, v73
	v_mul_f32_e32 v72, 0x3fb8aa3b, v72
	v_exp_f32_e32 v226, v156
	v_max_f32_e32 v156, v227, v73
	v_exp_f32_e32 v72, v72
	v_sub_f32_e32 v225, v227, v156
	v_sub_f32_e32 v73, v73, v156
	v_mul_f32_e32 v225, 0x3fb8aa3b, v225
	v_mul_f32_e32 v73, 0x3fb8aa3b, v73
	v_exp_f32_e32 v238, v225
	v_exp_f32_e32 v240, v73
	v_fma_f32 v73, v223, v72, v224
	v_fma_f32 v73, v73, v226, v236
	v_pk_mul_f32 v[50:51], v[50:51], v[236:237] op_sel_hi:[1,0]
	v_fma_f32 v223, v73, v238, v240
	v_add_f32_e32 v73, v76, v77
	s_waitcnt vmcnt(35)
	v_add_f32_e32 v73, v221, v73
	v_max_f32_e32 v225, v156, v73
	v_sub_f32_e32 v73, v73, v225
	v_sub_f32_e32 v76, v156, v225
	v_mul_f32_e32 v73, 0x3fb8aa3b, v73
	v_mul_f32_e32 v76, 0x3fb8aa3b, v76
	v_exp_f32_e32 v156, v73
	v_exp_f32_e32 v242, v76
	v_pk_mul_f32 v[42:43], v[42:43], v[224:225] op_sel_hi:[1,0]
	s_add_i32 s3, s3, 8
	v_pk_fma_f32 v[42:43], v[218:219], v[72:73], v[42:43] op_sel_hi:[1,0,1]
	v_pk_mul_f32 v[6:7], v[6:7], v[156:157] op_sel_hi:[1,0]
	v_pk_fma_f32 v[42:43], v[42:43], v[226:227], v[50:51] op_sel_hi:[1,0,1]
	v_pk_mul_f32 v[50:51], v[58:59], v[240:241] op_sel_hi:[1,0]
	v_pk_mul_f32 v[8:9], v[8:9], v[156:157] op_sel_hi:[1,0]
	v_pk_fma_f32 v[42:43], v[42:43], v[238:239], v[50:51] op_sel_hi:[1,0,1]
	v_pk_mul_f32 v[2:3], v[2:3], v[156:157] op_sel_hi:[1,0]
	v_pk_fma_f32 v[42:43], v[42:43], v[242:243], v[6:7] op_sel_hi:[1,0,1]
	v_pk_mul_f32 v[6:7], v[44:45], v[224:225] op_sel_hi:[1,0]
	v_pk_mul_f32 v[44:45], v[52:53], v[236:237] op_sel_hi:[1,0]
	v_pk_fma_f32 v[6:7], v[216:217], v[72:73], v[6:7] op_sel_hi:[1,0,1]
	v_pk_mul_f32 v[4:5], v[4:5], v[156:157] op_sel_hi:[1,0]
	v_pk_fma_f32 v[6:7], v[6:7], v[226:227], v[44:45] op_sel_hi:[1,0,1]
	v_pk_mul_f32 v[44:45], v[60:61], v[240:241] op_sel_hi:[1,0]
	v_fmac_f32_e32 v156, v223, v242
	v_pk_fma_f32 v[6:7], v[6:7], v[238:239], v[44:45] op_sel_hi:[1,0,1]
	s_cmp_gt_u32 s3, 39
	v_pk_fma_f32 v[44:45], v[6:7], v[242:243], v[8:9] op_sel_hi:[1,0,1]
	v_pk_mul_f32 v[6:7], v[34:35], v[224:225] op_sel_hi:[1,0]
	v_pk_mul_f32 v[8:9], v[38:39], v[236:237] op_sel_hi:[1,0]
	v_pk_fma_f32 v[6:7], v[212:213], v[72:73], v[6:7] op_sel_hi:[1,0,1]
	v_min_i32_e32 v38, 0x187, v254
	v_pk_fma_f32 v[6:7], v[6:7], v[226:227], v[8:9] op_sel_hi:[1,0,1]
	v_pk_mul_f32 v[8:9], v[46:47], v[240:241] op_sel_hi:[1,0]
	v_ashrrev_i32_e32 v39, 31, v38
	v_pk_fma_f32 v[6:7], v[6:7], v[238:239], v[8:9] op_sel_hi:[1,0,1]
	v_lshl_add_u64 v[38:39], v[38:39], 2, s[30:31]
	v_pk_fma_f32 v[34:35], v[6:7], v[242:243], v[2:3] op_sel_hi:[1,0,1]
	v_pk_mul_f32 v[2:3], v[36:37], v[224:225] op_sel_hi:[1,0]
	v_pk_mul_f32 v[6:7], v[40:41], v[236:237] op_sel_hi:[1,0]
	v_pk_fma_f32 v[2:3], v[214:215], v[72:73], v[2:3] op_sel_hi:[1,0,1]
	s_waitcnt vmcnt(33)
; __device__ __forceinline__ void p_attn_sample(const float* P, const float* ck, const float* cv, const float* relb, bf16* heads, const float* sbt, unsigned* qctr, volatile LAS unsigned* slot, int wave, int lane_in) {
;     ...
;         SLOADB(ak0, ak1, av0, av1, ab, 0)
	v_pk_mul_f32 v[40:41], v[204:205], v[114:115]
	v_pk_fma_f32 v[2:3], v[2:3], v[226:227], v[6:7] op_sel_hi:[1,0,1]
	v_pk_mul_f32 v[6:7], v[48:49], v[240:241] op_sel_hi:[1,0]
	v_add_u32_e32 v222, 64, v222
	v_pk_fma_f32 v[2:3], v[2:3], v[238:239], v[6:7] op_sel_hi:[1,0,1]
	s_nop 0
	v_pk_fma_f32 v[36:37], v[2:3], v[242:243], v[4:5] op_sel_hi:[1,0,1]
	v_lshl_add_u64 v[2:3], v[74:75], 0, s[28:29]
	v_lshl_add_u64 v[4:5], v[198:199], 0, v[70:71]
	v_cndmask_b32_e32 v7, v5, v3, vcc
	v_cndmask_b32_e32 v6, v4, v2, vcc
	global_load_dwordx4 v[70:73], v[74:75], off offset:16
	s_nop 0
	global_load_dwordx4 v[74:77], v[74:75], off
	s_nop 0
	global_load_dwordx4 v[2:5], v[6:7], off offset:16
	s_nop 0
	global_load_dwordx4 v[6:9], v[6:7], off
	s_nop 0
	global_load_dword v221, v[38:39], off
	v_pk_mul_f32 v[38:39], v[206:207], v[116:117]
	s_nop 0
	v_pk_mov_b32 v[46:47], v[40:41], v[38:39] op_sel:[1,0]
	v_mov_b32_e32 v41, v39
	v_pk_add_f32 v[38:39], v[46:47], v[40:41]
	v_pk_mul_f32 v[40:41], v[202:203], v[104:105]
	v_pk_mul_f32 v[46:47], v[200:201], v[102:103]
	v_mov_b32_e32 v48, v40
	v_mov_b32_e32 v49, v46
	v_mov_b32_e32 v46, v41
	v_pk_add_f32 v[40:41], v[48:49], v[46:47]
	v_add_f32_e32 v38, v38, v39
	v_add_f32_e32 v38, v38, v41
	v_add_f32_e32 v38, v40, v38
	s_waitcnt vmcnt(33)
	v_pk_mul_f32 v[46:47], v[206:207], v[124:125]
	v_pk_mul_f32 v[48:49], v[204:205], v[122:123]
	v_add_f32_dpp v38, v38, v38 quad_perm:[1,0,3,2] row_mask:0xf bank_mask:0xf bound_ctrl:1
	v_pk_mov_b32 v[50:51], v[48:49], v[46:47] op_sel:[1,0]
	v_mov_b32_e32 v49, v47
	v_add_f32_dpp v38, v38, v38 quad_perm:[2,3,0,1] row_mask:0xf bank_mask:0xf bound_ctrl:1
	v_pk_add_f32 v[46:47], v[50:51], v[48:49]
	v_pk_mul_f32 v[48:49], v[202:203], v[120:121]
	v_add_f32_dpp v38, v38, v38 row_half_mirror row_mask:0xf bank_mask:0xf bound_ctrl:1
	v_add_f32_e32 v39, v228, v38
	v_max_f32_e32 v41, v225, v39
	v_sub_f32_e32 v39, v39, v41
	v_pk_mul_f32 v[50:51], v[200:201], v[118:119]
	v_mul_f32_e32 v39, 0x3fb8aa3b, v39
	v_mov_b32_e32 v52, v48
	v_mov_b32_e32 v53, v50
	v_mov_b32_e32 v50, v49
	v_exp_f32_e32 v40, v39
	v_pk_add_f32 v[48:49], v[52:53], v[50:51]
	v_add_f32_e32 v39, v46, v47
	v_add_f32_e32 v39, v39, v49
	v_add_f32_e32 v39, v48, v39
	s_waitcnt vmcnt(28)
	v_pk_mul_f32 v[50:51], v[206:207], v[140:141]
	v_pk_mul_f32 v[52:53], v[204:205], v[138:139]
	v_add_f32_dpp v39, v39, v39 quad_perm:[1,0,3,2] row_mask:0xf bank_mask:0xf bound_ctrl:1
	v_pk_mov_b32 v[58:59], v[52:53], v[50:51] op_sel:[1,0]
	v_mov_b32_e32 v53, v51
	v_add_f32_dpp v39, v39, v39 quad_perm:[2,3,0,1] row_mask:0xf bank_mask:0xf bound_ctrl:1
	v_pk_add_f32 v[50:51], v[58:59], v[52:53]
	v_pk_mul_f32 v[52:53], v[202:203], v[136:137]
	v_add_f32_dpp v39, v39, v39 row_half_mirror row_mask:0xf bank_mask:0xf bound_ctrl:1
	v_add_f32_e32 v39, v229, v39
	v_max_f32_e32 v47, v41, v39
	v_sub_f32_e32 v39, v39, v47
	v_pk_mul_f32 v[58:59], v[200:201], v[134:135]
	v_mul_f32_e32 v39, 0x3fb8aa3b, v39
	v_mov_b32_e32 v60, v52
	v_mov_b32_e32 v61, v58
	v_mov_b32_e32 v58, v53
	v_exp_f32_e32 v48, v39
	v_pk_add_f32 v[52:53], v[60:61], v[58:59]
	v_add_f32_e32 v39, v50, v51
	v_add_f32_e32 v39, v39, v53
	v_add_f32_e32 v39, v52, v39
	v_sub_f32_e32 v38, v225, v41
	v_sub_f32_e32 v41, v41, v47
	v_add_f32_dpp v39, v39, v39 quad_perm:[1,0,3,2] row_mask:0xf bank_mask:0xf bound_ctrl:1
	v_mul_f32_e32 v41, 0x3fb8aa3b, v41
	s_waitcnt vmcnt(23)
; __device__ __forceinline__ void p_attn_sample(const float* P, const float* ck, const float* cv, const float* relb, bf16* heads, const float* sbt, unsigned* qctr, volatile LAS unsigned* slot, int wave, int lane_in) {
;     ...
;         SLOADB(ak0, ak1, av0, av1, ab, 0)
; #pragma unroll 1
;         for (int it0 = 0; it0 < 48; it0 += 8) {
;             SLOADB(bk0, bk1, bv0, bv1, bbv, it0 + 4)
;             SPROCB(ak0, ak1, av0, av1, ab)
;             SLOADB(ak0, ak1, av0, av1, ab, it0 + 8)
;             SPROCB(bk0, bk1, bv0, bv1, bbv)
;         }
	v_pk_mul_f32 v[58:59], v[206:207], v[148:149]
	v_add_f32_dpp v39, v39, v39 quad_perm:[2,3,0,1] row_mask:0xf bank_mask:0xf bound_ctrl:1
	v_pk_mul_f32 v[60:61], v[204:205], v[146:147]
	v_exp_f32_e32 v46, v41
	v_add_f32_dpp v39, v39, v39 row_half_mirror row_mask:0xf bank_mask:0xf bound_ctrl:1
	v_add_f32_e32 v39, v230, v39
	v_max_f32_e32 v41, v47, v39
	v_pk_mov_b32 v[102:103], v[60:61], v[58:59] op_sel:[1,0]
	v_mov_b32_e32 v61, v59
	v_sub_f32_e32 v39, v39, v41
	v_pk_add_f32 v[58:59], v[102:103], v[60:61]
	v_pk_mul_f32 v[60:61], v[202:203], v[144:145]
	v_pk_mul_f32 v[102:103], v[200:201], v[142:143]
	v_mul_f32_e32 v39, 0x3fb8aa3b, v39
	v_mov_b32_e32 v104, v60
	v_mov_b32_e32 v105, v102
	v_mov_b32_e32 v102, v61
	v_exp_f32_e32 v52, v39
	v_pk_add_f32 v[60:61], v[104:105], v[102:103]
	v_add_f32_e32 v39, v58, v59
	v_add_f32_e32 v39, v39, v61
	v_add_f32_e32 v39, v60, v39
	v_mul_f32_e32 v38, 0x3fb8aa3b, v38
	v_exp_f32_e32 v38, v38
	v_add_f32_dpp v39, v39, v39 quad_perm:[1,0,3,2] row_mask:0xf bank_mask:0xf bound_ctrl:1
	v_sub_f32_e32 v47, v47, v41
	v_mul_f32_e32 v47, 0x3fb8aa3b, v47
	v_add_f32_dpp v39, v39, v39 quad_perm:[2,3,0,1] row_mask:0xf bank_mask:0xf bound_ctrl:1
	v_exp_f32_e32 v50, v47
	s_nop 0
	v_add_f32_dpp v39, v39, v39 row_half_mirror row_mask:0xf bank_mask:0xf bound_ctrl:1
	s_waitcnt vmcnt(20)
	v_add_f32_e32 v39, v231, v39
	v_max_f32_e32 v224, v41, v39
	v_sub_f32_e32 v39, v39, v224
	v_mul_f32_e32 v39, 0x3fb8aa3b, v39
	v_sub_f32_e32 v41, v41, v224
	v_exp_f32_e32 v60, v39
	v_fma_f32 v39, v156, v38, v40
	v_mul_f32_e32 v41, 0x3fb8aa3b, v41
	v_fma_f32 v39, v39, v46, v48
	v_exp_f32_e32 v58, v41
	v_fma_f32 v39, v39, v50, v52
	v_pk_mul_f32 v[62:63], v[62:63], v[40:41] op_sel_hi:[1,0]
	v_fma_f32 v223, v39, v58, v60
	v_pk_fma_f32 v[42:43], v[42:43], v[38:39], v[62:63] op_sel_hi:[1,0,1]
	v_pk_mul_f32 v[62:63], v[78:79], v[48:49] op_sel_hi:[1,0]
	s_nop 0
	v_pk_fma_f32 v[42:43], v[42:43], v[46:47], v[62:63] op_sel_hi:[1,0,1]
	v_pk_mul_f32 v[62:63], v[94:95], v[52:53] op_sel_hi:[1,0]
	s_nop 0
	v_pk_fma_f32 v[42:43], v[42:43], v[50:51], v[62:63] op_sel_hi:[1,0,1]
	v_pk_mul_f32 v[62:63], v[126:127], v[60:61] op_sel_hi:[1,0]
	s_nop 0
	v_pk_fma_f32 v[218:219], v[42:43], v[58:59], v[62:63] op_sel_hi:[1,0,1]
	v_pk_mul_f32 v[42:43], v[64:65], v[40:41] op_sel_hi:[1,0]
	s_nop 0
	v_pk_fma_f32 v[42:43], v[44:45], v[38:39], v[42:43] op_sel_hi:[1,0,1]
	v_pk_mul_f32 v[44:45], v[80:81], v[48:49] op_sel_hi:[1,0]
	s_nop 0
	v_pk_fma_f32 v[42:43], v[42:43], v[46:47], v[44:45] op_sel_hi:[1,0,1]
	v_pk_mul_f32 v[44:45], v[96:97], v[52:53] op_sel_hi:[1,0]
	s_nop 0
	v_pk_fma_f32 v[42:43], v[42:43], v[50:51], v[44:45] op_sel_hi:[1,0,1]
	v_pk_mul_f32 v[44:45], v[128:129], v[60:61] op_sel_hi:[1,0]
	s_nop 0
	v_pk_fma_f32 v[216:217], v[42:43], v[58:59], v[44:45] op_sel_hi:[1,0,1]
	v_pk_mul_f32 v[42:43], v[54:55], v[40:41] op_sel_hi:[1,0]
	s_nop 0
	v_pk_fma_f32 v[34:35], v[34:35], v[38:39], v[42:43] op_sel_hi:[1,0,1]
	v_pk_mul_f32 v[42:43], v[66:67], v[48:49] op_sel_hi:[1,0]
	s_nop 0
	v_pk_fma_f32 v[34:35], v[34:35], v[46:47], v[42:43] op_sel_hi:[1,0,1]
	v_pk_mul_f32 v[42:43], v[86:87], v[52:53] op_sel_hi:[1,0]
	s_nop 0
	v_pk_fma_f32 v[34:35], v[34:35], v[50:51], v[42:43] op_sel_hi:[1,0,1]
	v_pk_mul_f32 v[42:43], v[110:111], v[60:61] op_sel_hi:[1,0]
	s_nop 0
	v_pk_fma_f32 v[212:213], v[34:35], v[58:59], v[42:43] op_sel_hi:[1,0,1]
	v_pk_mul_f32 v[34:35], v[56:57], v[40:41] op_sel_hi:[1,0]
	s_nop 0
	v_pk_fma_f32 v[34:35], v[36:37], v[38:39], v[34:35] op_sel_hi:[1,0,1]
	v_pk_mul_f32 v[36:37], v[68:69], v[48:49] op_sel_hi:[1,0]
	s_nop 0
	v_pk_fma_f32 v[34:35], v[34:35], v[46:47], v[36:37] op_sel_hi:[1,0,1]
	v_pk_mul_f32 v[36:37], v[88:89], v[52:53] op_sel_hi:[1,0]
	s_nop 0
	v_pk_fma_f32 v[34:35], v[34:35], v[50:51], v[36:37] op_sel_hi:[1,0,1]
	v_pk_mul_f32 v[36:37], v[112:113], v[60:61] op_sel_hi:[1,0]
	s_nop 0
	v_pk_fma_f32 v[214:215], v[34:35], v[58:59], v[36:37] op_sel_hi:[1,0,1]
	s_cbranch_scc1 .LBB0_1417
	s_waitcnt vmcnt(17)
	v_mov_b64_e32 v[34:35], v[90:91]
	s_waitcnt vmcnt(12)
	v_mov_b64_e32 v[38:39], v[82:83]
	s_waitcnt vmcnt(7)
	v_mov_b64_e32 v[46:47], v[106:107]
	v_mov_b64_e32 v[42:43], v[150:151]
	v_mov_b64_e32 v[50:51], v[98:99]
	s_waitcnt vmcnt(6)
	v_mov_b64_e32 v[58:59], v[130:131]
	v_mov_b64_e32 v[36:37], v[92:93]
	v_mov_b64_e32 v[40:41], v[84:85]
	v_mov_b64_e32 v[48:49], v[108:109]
	v_mov_b64_e32 v[44:45], v[152:153]
	v_mov_b64_e32 v[52:53], v[100:101]
	v_mov_b64_e32 v[60:61], v[132:133]
	s_waitcnt vmcnt(5)
	v_mov_b32_e32 v225, v234
	v_mov_b32_e32 v226, v233
	v_mov_b32_e32 v227, v232
	s_branch .LBB0_1383
